# RG-LRU scan loop rewritten: LDS loads hoisted 5 steps ahead (d16_hi into zeroed regs), same arithmetic
# speedup vs baseline: 1.0287x; 1.0287x over previous
; #define LAS __attribute__((address_space(3)))
; DI unsigned pk2(float a, float b) { f32x2 v = {a, b}; bf2_t r = __builtin_convertvector(v, bf2_t); return __builtin_bit_cast(unsigned, r); }
; DI void phase_rglru(const Params& p, unsigned char* shm) {
;     ...
;             if (tid < 192) {
; #pragma unroll 8
;                 for (int r = 0; r < 64; ++r) {
;                     const float om = __uint_as_float((unsigned)*(const LAS bf16_t*)(lds + LAo + r * TR + tid * 2) << 16);
;                     const float bt = __uint_as_float((unsigned)*(const LAS bf16_t*)(lds + BTo + r * TR + tid * 2) << 16);
;                     const float g = __uint_as_float((unsigned)*(const LAS bf16_t*)(lds + GT + r * TR + tid * 2) << 16);
;                     hst = (hst - om * hst) + bt;
;                     *(LAS bf16_t*)(lds + GT + r * TR + tid * 2) = (bf16_t)(pk2(hst * g, 0.f) & 0xffffu);
;                 }
.LBB0_851:
	s_andn2_saveexec_b64 s[2:3], s[2:3]
	s_cbranch_execz .LBB0_842
	v_mov_b32_e32 v126, 0
	v_mov_b32_e32 v127, 0
	v_mov_b32_e32 v128, 0
	v_mov_b32_e32 v129, 0
	v_mov_b32_e32 v130, 0
	v_mov_b32_e32 v131, 0
	v_mov_b32_e32 v132, 0
	v_mov_b32_e32 v133, 0
	v_mov_b32_e32 v134, 0
	v_mov_b32_e32 v135, 0
	v_mov_b32_e32 v136, 0
	v_mov_b32_e32 v137, 0
	v_mov_b32_e32 v138, 0
	v_mov_b32_e32 v139, 0
	v_mov_b32_e32 v140, 0
	v_mov_b32_e32 v141, 0
	v_mov_b32_e32 v142, 0
	v_mov_b32_e32 v143, 0
	v_mov_b32_e32 v144, 0
	v_mov_b32_e32 v145, 0
	v_mov_b32_e32 v146, 0
	v_mov_b32_e32 v147, 0
	v_mov_b32_e32 v148, 0
	v_mov_b32_e32 v149, 0
	v_add_u32_e32 v121, 0x13100, v176
	v_add_u32_e32 v122, 0x19500, v176
	v_add_u32_e32 v123, 0xcd00, v176
	ds_read_u16_d16_hi v126, v121
	ds_read_u16_d16_hi v134, v122
	ds_read_u16_d16_hi v142, v123
	ds_read_u16_d16_hi v127, v121 offset:400
	ds_read_u16_d16_hi v135, v122 offset:400
	ds_read_u16_d16_hi v143, v123 offset:400
	ds_read_u16_d16_hi v128, v121 offset:800
	ds_read_u16_d16_hi v136, v122 offset:800
	ds_read_u16_d16_hi v144, v123 offset:800
	ds_read_u16_d16_hi v129, v121 offset:1200
	ds_read_u16_d16_hi v137, v122 offset:1200
	ds_read_u16_d16_hi v145, v123 offset:1200
	ds_read_u16_d16_hi v130, v121 offset:1600
	ds_read_u16_d16_hi v138, v122 offset:1600
	ds_read_u16_d16_hi v146, v123 offset:1600
	s_waitcnt lgkmcnt(12)
	v_fma_f32 v150, -v152, v126, v152
	v_add_f32_e32 v152, v150, v134
	v_mul_f32_e32 v170, v152, v142
	ds_read_u16_d16_hi v131, v121 offset:2000
	ds_read_u16_d16_hi v139, v122 offset:2000
	ds_read_u16_d16_hi v147, v123 offset:2000
	s_waitcnt lgkmcnt(12)
	v_fma_f32 v150, -v152, v127, v152
	v_add_f32_e32 v152, v150, v135
	v_mul_f32_e32 v171, v152, v143
	ds_read_u16_d16_hi v132, v121 offset:2400
	ds_read_u16_d16_hi v140, v122 offset:2400
	ds_read_u16_d16_hi v148, v123 offset:2400
	v_cvt_pk_bf16_f32 v151, v170, v171
	ds_write_b16 v123, v151
	ds_write_b16_d16_hi v123, v151 offset:400
	s_waitcnt lgkmcnt(14)
	v_fma_f32 v150, -v152, v128, v152
	v_add_f32_e32 v152, v150, v136
	v_mul_f32_e32 v170, v152, v144
	ds_read_u16_d16_hi v133, v121 offset:2800
	ds_read_u16_d16_hi v141, v122 offset:2800
	ds_read_u16_d16_hi v149, v123 offset:2800
	s_waitcnt lgkmcnt(14)
	v_fma_f32 v150, -v152, v129, v152
	v_add_f32_e32 v152, v150, v137
	v_mul_f32_e32 v171, v152, v145
	ds_read_u16_d16_hi v126, v121 offset:3200
	ds_read_u16_d16_hi v134, v122 offset:3200
	ds_read_u16_d16_hi v142, v123 offset:3200
	v_cvt_pk_bf16_f32 v151, v170, v171
	ds_write_b16 v123, v151 offset:800
	ds_write_b16_d16_hi v123, v151 offset:1200
	s_waitcnt lgkmcnt(15)
	v_fma_f32 v150, -v152, v130, v152
	v_add_f32_e32 v152, v150, v138
	v_mul_f32_e32 v170, v152, v146
	ds_read_u16_d16_hi v127, v121 offset:3600
	ds_read_u16_d16_hi v135, v122 offset:3600
	ds_read_u16_d16_hi v143, v123 offset:3600
	s_waitcnt lgkmcnt(15)
	v_fma_f32 v150, -v152, v131, v152
	v_add_f32_e32 v152, v150, v139
	v_mul_f32_e32 v171, v152, v147
	ds_read_u16_d16_hi v128, v121 offset:4000
	ds_read_u16_d16_hi v136, v122 offset:4000
	ds_read_u16_d16_hi v144, v123 offset:4000
	v_cvt_pk_bf16_f32 v151, v170, v171
	ds_write_b16 v123, v151 offset:1600
	ds_write_b16_d16_hi v123, v151 offset:2000
	s_waitcnt lgkmcnt(15)
	v_fma_f32 v150, -v152, v132, v152
	v_add_f32_e32 v152, v150, v140
	v_mul_f32_e32 v170, v152, v148
	ds_read_u16_d16_hi v129, v121 offset:4400
	ds_read_u16_d16_hi v137, v122 offset:4400
	ds_read_u16_d16_hi v145, v123 offset:4400
	s_waitcnt lgkmcnt(15)
	v_fma_f32 v150, -v152, v133, v152
	v_add_f32_e32 v152, v150, v141
	v_mul_f32_e32 v171, v152, v149
	ds_read_u16_d16_hi v130, v121 offset:4800
	ds_read_u16_d16_hi v138, v122 offset:4800
	ds_read_u16_d16_hi v146, v123 offset:4800
	v_cvt_pk_bf16_f32 v151, v170, v171
	ds_write_b16 v123, v151 offset:2400
	ds_write_b16_d16_hi v123, v151 offset:2800
	s_waitcnt lgkmcnt(15)
	v_fma_f32 v150, -v152, v126, v152
	v_add_f32_e32 v152, v150, v134
	v_mul_f32_e32 v170, v152, v142
	ds_read_u16_d16_hi v131, v121 offset:5200
	ds_read_u16_d16_hi v139, v122 offset:5200
	ds_read_u16_d16_hi v147, v123 offset:5200
	s_waitcnt lgkmcnt(15)
	v_fma_f32 v150, -v152, v127, v152
	v_add_f32_e32 v152, v150, v135
	v_mul_f32_e32 v171, v152, v143
	ds_read_u16_d16_hi v132, v121 offset:5600
	ds_read_u16_d16_hi v140, v122 offset:5600
	ds_read_u16_d16_hi v148, v123 offset:5600
	v_cvt_pk_bf16_f32 v151, v170, v171
	ds_write_b16 v123, v151 offset:3200
	ds_write_b16_d16_hi v123, v151 offset:3600
	s_waitcnt lgkmcnt(15)
	v_fma_f32 v150, -v152, v128, v152
	v_add_f32_e32 v152, v150, v136
	v_mul_f32_e32 v170, v152, v144
	ds_read_u16_d16_hi v133, v121 offset:6000
	ds_read_u16_d16_hi v141, v122 offset:6000
	ds_read_u16_d16_hi v149, v123 offset:6000
	s_waitcnt lgkmcnt(15)
	v_fma_f32 v150, -v152, v129, v152
	v_add_f32_e32 v152, v150, v137
	v_mul_f32_e32 v171, v152, v145
	ds_read_u16_d16_hi v126, v121 offset:6400
	ds_read_u16_d16_hi v134, v122 offset:6400
	ds_read_u16_d16_hi v142, v123 offset:6400
	v_cvt_pk_bf16_f32 v151, v170, v171
	ds_write_b16 v123, v151 offset:4000
	ds_write_b16_d16_hi v123, v151 offset:4400
	s_waitcnt lgkmcnt(15)
	v_fma_f32 v150, -v152, v130, v152
	v_add_f32_e32 v152, v150, v138
	v_mul_f32_e32 v170, v152, v146
	ds_read_u16_d16_hi v127, v121 offset:6800
	ds_read_u16_d16_hi v135, v122 offset:6800
	ds_read_u16_d16_hi v143, v123 offset:6800
	s_waitcnt lgkmcnt(15)
	v_fma_f32 v150, -v152, v131, v152
	v_add_f32_e32 v152, v150, v139
	v_mul_f32_e32 v171, v152, v147
	ds_read_u16_d16_hi v128, v121 offset:7200
	ds_read_u16_d16_hi v136, v122 offset:7200
	ds_read_u16_d16_hi v144, v123 offset:7200
	v_cvt_pk_bf16_f32 v151, v170, v171
	ds_write_b16 v123, v151 offset:4800
	ds_write_b16_d16_hi v123, v151 offset:5200
	s_waitcnt lgkmcnt(15)
; #define LAS __attribute__((address_space(3)))
; DI unsigned pk2(float a, float b) { f32x2 v = {a, b}; bf2_t r = __builtin_convertvector(v, bf2_t); return __builtin_bit_cast(unsigned, r); }
; DI void phase_rglru(const Params& p, unsigned char* shm) {
;     ...
;             if (tid < 192) {
; #pragma unroll 8
;                 for (int r = 0; r < 64; ++r) {
;                     const float om = __uint_as_float((unsigned)*(const LAS bf16_t*)(lds + LAo + r * TR + tid * 2) << 16);
;                     const float bt = __uint_as_float((unsigned)*(const LAS bf16_t*)(lds + BTo + r * TR + tid * 2) << 16);
;                     const float g = __uint_as_float((unsigned)*(const LAS bf16_t*)(lds + GT + r * TR + tid * 2) << 16);
;                     hst = (hst - om * hst) + bt;
;                     *(LAS bf16_t*)(lds + GT + r * TR + tid * 2) = (bf16_t)(pk2(hst * g, 0.f) & 0xffffu);
;                 }
	v_fma_f32 v150, -v152, v132, v152
	v_add_f32_e32 v152, v150, v140
	v_mul_f32_e32 v170, v152, v148
	ds_read_u16_d16_hi v129, v121 offset:7600
	ds_read_u16_d16_hi v137, v122 offset:7600
	ds_read_u16_d16_hi v145, v123 offset:7600
	s_waitcnt lgkmcnt(15)
	v_fma_f32 v150, -v152, v133, v152
	v_add_f32_e32 v152, v150, v141
	v_mul_f32_e32 v171, v152, v149
	ds_read_u16_d16_hi v130, v121 offset:8000
	ds_read_u16_d16_hi v138, v122 offset:8000
	ds_read_u16_d16_hi v146, v123 offset:8000
	v_cvt_pk_bf16_f32 v151, v170, v171
	ds_write_b16 v123, v151 offset:5600
	ds_write_b16_d16_hi v123, v151 offset:6000
	s_waitcnt lgkmcnt(15)
	v_fma_f32 v150, -v152, v126, v152
	v_add_f32_e32 v152, v150, v134
	v_mul_f32_e32 v170, v152, v142
	ds_read_u16_d16_hi v131, v121 offset:8400
	ds_read_u16_d16_hi v139, v122 offset:8400
	ds_read_u16_d16_hi v147, v123 offset:8400
	s_waitcnt lgkmcnt(15)
	v_fma_f32 v150, -v152, v127, v152
	v_add_f32_e32 v152, v150, v135
	v_mul_f32_e32 v171, v152, v143
	ds_read_u16_d16_hi v132, v121 offset:8800
	ds_read_u16_d16_hi v140, v122 offset:8800
	ds_read_u16_d16_hi v148, v123 offset:8800
	v_cvt_pk_bf16_f32 v151, v170, v171
	ds_write_b16 v123, v151 offset:6400
	ds_write_b16_d16_hi v123, v151 offset:6800
	s_waitcnt lgkmcnt(15)
	v_fma_f32 v150, -v152, v128, v152
	v_add_f32_e32 v152, v150, v136
	v_mul_f32_e32 v170, v152, v144
	ds_read_u16_d16_hi v133, v121 offset:9200
	ds_read_u16_d16_hi v141, v122 offset:9200
	ds_read_u16_d16_hi v149, v123 offset:9200
	s_waitcnt lgkmcnt(15)
	v_fma_f32 v150, -v152, v129, v152
	v_add_f32_e32 v152, v150, v137
	v_mul_f32_e32 v171, v152, v145
	ds_read_u16_d16_hi v126, v121 offset:9600
	ds_read_u16_d16_hi v134, v122 offset:9600
	ds_read_u16_d16_hi v142, v123 offset:9600
	v_cvt_pk_bf16_f32 v151, v170, v171
	ds_write_b16 v123, v151 offset:7200
	ds_write_b16_d16_hi v123, v151 offset:7600
	s_waitcnt lgkmcnt(15)
	v_fma_f32 v150, -v152, v130, v152
	v_add_f32_e32 v152, v150, v138
	v_mul_f32_e32 v170, v152, v146
	ds_read_u16_d16_hi v127, v121 offset:10000
	ds_read_u16_d16_hi v135, v122 offset:10000
	ds_read_u16_d16_hi v143, v123 offset:10000
	s_waitcnt lgkmcnt(15)
	v_fma_f32 v150, -v152, v131, v152
	v_add_f32_e32 v152, v150, v139
	v_mul_f32_e32 v171, v152, v147
	ds_read_u16_d16_hi v128, v121 offset:10400
	ds_read_u16_d16_hi v136, v122 offset:10400
	ds_read_u16_d16_hi v144, v123 offset:10400
	v_cvt_pk_bf16_f32 v151, v170, v171
	ds_write_b16 v123, v151 offset:8000
	ds_write_b16_d16_hi v123, v151 offset:8400
	s_waitcnt lgkmcnt(15)
	v_fma_f32 v150, -v152, v132, v152
	v_add_f32_e32 v152, v150, v140
	v_mul_f32_e32 v170, v152, v148
	ds_read_u16_d16_hi v129, v121 offset:10800
	ds_read_u16_d16_hi v137, v122 offset:10800
	ds_read_u16_d16_hi v145, v123 offset:10800
	s_waitcnt lgkmcnt(15)
	v_fma_f32 v150, -v152, v133, v152
	v_add_f32_e32 v152, v150, v141
	v_mul_f32_e32 v171, v152, v149
	ds_read_u16_d16_hi v130, v121 offset:11200
	ds_read_u16_d16_hi v138, v122 offset:11200
	ds_read_u16_d16_hi v146, v123 offset:11200
	v_cvt_pk_bf16_f32 v151, v170, v171
	ds_write_b16 v123, v151 offset:8800
	ds_write_b16_d16_hi v123, v151 offset:9200
	s_waitcnt lgkmcnt(15)
	v_fma_f32 v150, -v152, v126, v152
	v_add_f32_e32 v152, v150, v134
	v_mul_f32_e32 v170, v152, v142
	ds_read_u16_d16_hi v131, v121 offset:11600
	ds_read_u16_d16_hi v139, v122 offset:11600
	ds_read_u16_d16_hi v147, v123 offset:11600
	s_waitcnt lgkmcnt(15)
	v_fma_f32 v150, -v152, v127, v152
	v_add_f32_e32 v152, v150, v135
	v_mul_f32_e32 v171, v152, v143
	ds_read_u16_d16_hi v132, v121 offset:12000
	ds_read_u16_d16_hi v140, v122 offset:12000
	ds_read_u16_d16_hi v148, v123 offset:12000
	v_cvt_pk_bf16_f32 v151, v170, v171
	ds_write_b16 v123, v151 offset:9600
	ds_write_b16_d16_hi v123, v151 offset:10000
	s_waitcnt lgkmcnt(15)
	v_fma_f32 v150, -v152, v128, v152
	v_add_f32_e32 v152, v150, v136
	v_mul_f32_e32 v170, v152, v144
	ds_read_u16_d16_hi v133, v121 offset:12400
	ds_read_u16_d16_hi v141, v122 offset:12400
	ds_read_u16_d16_hi v149, v123 offset:12400
	s_waitcnt lgkmcnt(15)
	v_fma_f32 v150, -v152, v129, v152
	v_add_f32_e32 v152, v150, v137
	v_mul_f32_e32 v171, v152, v145
	ds_read_u16_d16_hi v126, v121 offset:12800
	ds_read_u16_d16_hi v134, v122 offset:12800
	ds_read_u16_d16_hi v142, v123 offset:12800
	v_cvt_pk_bf16_f32 v151, v170, v171
	ds_write_b16 v123, v151 offset:10400
	ds_write_b16_d16_hi v123, v151 offset:10800
	s_waitcnt lgkmcnt(15)
	v_fma_f32 v150, -v152, v130, v152
	v_add_f32_e32 v152, v150, v138
	v_mul_f32_e32 v170, v152, v146
	ds_read_u16_d16_hi v127, v121 offset:13200
	ds_read_u16_d16_hi v135, v122 offset:13200
	ds_read_u16_d16_hi v143, v123 offset:13200
	s_waitcnt lgkmcnt(15)
	v_fma_f32 v150, -v152, v131, v152
	v_add_f32_e32 v152, v150, v139
	v_mul_f32_e32 v171, v152, v147
	ds_read_u16_d16_hi v128, v121 offset:13600
	ds_read_u16_d16_hi v136, v122 offset:13600
	ds_read_u16_d16_hi v144, v123 offset:13600
	v_cvt_pk_bf16_f32 v151, v170, v171
	ds_write_b16 v123, v151 offset:11200
	ds_write_b16_d16_hi v123, v151 offset:11600
	s_waitcnt lgkmcnt(15)
	v_fma_f32 v150, -v152, v132, v152
	v_add_f32_e32 v152, v150, v140
	v_mul_f32_e32 v170, v152, v148
	ds_read_u16_d16_hi v129, v121 offset:14000
	ds_read_u16_d16_hi v137, v122 offset:14000
	ds_read_u16_d16_hi v145, v123 offset:14000
	s_waitcnt lgkmcnt(15)
	v_fma_f32 v150, -v152, v133, v152
	v_add_f32_e32 v152, v150, v141
	v_mul_f32_e32 v171, v152, v149
	ds_read_u16_d16_hi v130, v121 offset:14400
	ds_read_u16_d16_hi v138, v122 offset:14400
	ds_read_u16_d16_hi v146, v123 offset:14400
	v_cvt_pk_bf16_f32 v151, v170, v171
	ds_write_b16 v123, v151 offset:12000
	ds_write_b16_d16_hi v123, v151 offset:12400
	s_waitcnt lgkmcnt(15)
; #define LAS __attribute__((address_space(3)))
; DI unsigned pk2(float a, float b) { f32x2 v = {a, b}; bf2_t r = __builtin_convertvector(v, bf2_t); return __builtin_bit_cast(unsigned, r); }
; DI void phase_rglru(const Params& p, unsigned char* shm) {
;     ...
;             if (tid < 192) {
; #pragma unroll 8
;                 for (int r = 0; r < 64; ++r) {
;                     const float om = __uint_as_float((unsigned)*(const LAS bf16_t*)(lds + LAo + r * TR + tid * 2) << 16);
;                     const float bt = __uint_as_float((unsigned)*(const LAS bf16_t*)(lds + BTo + r * TR + tid * 2) << 16);
;                     const float g = __uint_as_float((unsigned)*(const LAS bf16_t*)(lds + GT + r * TR + tid * 2) << 16);
;                     hst = (hst - om * hst) + bt;
;                     *(LAS bf16_t*)(lds + GT + r * TR + tid * 2) = (bf16_t)(pk2(hst * g, 0.f) & 0xffffu);
;                 }
	v_fma_f32 v150, -v152, v126, v152
	v_add_f32_e32 v152, v150, v134
	v_mul_f32_e32 v170, v152, v142
	ds_read_u16_d16_hi v131, v121 offset:14800
	ds_read_u16_d16_hi v139, v122 offset:14800
	ds_read_u16_d16_hi v147, v123 offset:14800
	s_waitcnt lgkmcnt(15)
	v_fma_f32 v150, -v152, v127, v152
	v_add_f32_e32 v152, v150, v135
	v_mul_f32_e32 v171, v152, v143
	ds_read_u16_d16_hi v132, v121 offset:15200
	ds_read_u16_d16_hi v140, v122 offset:15200
	ds_read_u16_d16_hi v148, v123 offset:15200
	v_cvt_pk_bf16_f32 v151, v170, v171
	ds_write_b16 v123, v151 offset:12800
	ds_write_b16_d16_hi v123, v151 offset:13200
	s_waitcnt lgkmcnt(15)
	v_fma_f32 v150, -v152, v128, v152
	v_add_f32_e32 v152, v150, v136
	v_mul_f32_e32 v170, v152, v144
	ds_read_u16_d16_hi v133, v121 offset:15600
	ds_read_u16_d16_hi v141, v122 offset:15600
	ds_read_u16_d16_hi v149, v123 offset:15600
	s_waitcnt lgkmcnt(15)
	v_fma_f32 v150, -v152, v129, v152
	v_add_f32_e32 v152, v150, v137
	v_mul_f32_e32 v171, v152, v145
	ds_read_u16_d16_hi v126, v121 offset:16000
	ds_read_u16_d16_hi v134, v122 offset:16000
	ds_read_u16_d16_hi v142, v123 offset:16000
	v_cvt_pk_bf16_f32 v151, v170, v171
	ds_write_b16 v123, v151 offset:13600
	ds_write_b16_d16_hi v123, v151 offset:14000
	s_waitcnt lgkmcnt(15)
	v_fma_f32 v150, -v152, v130, v152
	v_add_f32_e32 v152, v150, v138
	v_mul_f32_e32 v170, v152, v146
	ds_read_u16_d16_hi v127, v121 offset:16400
	ds_read_u16_d16_hi v135, v122 offset:16400
	ds_read_u16_d16_hi v143, v123 offset:16400
	s_waitcnt lgkmcnt(15)
	v_fma_f32 v150, -v152, v131, v152
	v_add_f32_e32 v152, v150, v139
	v_mul_f32_e32 v171, v152, v147
	ds_read_u16_d16_hi v128, v121 offset:16800
	ds_read_u16_d16_hi v136, v122 offset:16800
	ds_read_u16_d16_hi v144, v123 offset:16800
	v_cvt_pk_bf16_f32 v151, v170, v171
	ds_write_b16 v123, v151 offset:14400
	ds_write_b16_d16_hi v123, v151 offset:14800
	s_waitcnt lgkmcnt(15)
	v_fma_f32 v150, -v152, v132, v152
	v_add_f32_e32 v152, v150, v140
	v_mul_f32_e32 v170, v152, v148
	ds_read_u16_d16_hi v129, v121 offset:17200
	ds_read_u16_d16_hi v137, v122 offset:17200
	ds_read_u16_d16_hi v145, v123 offset:17200
	s_waitcnt lgkmcnt(15)
	v_fma_f32 v150, -v152, v133, v152
	v_add_f32_e32 v152, v150, v141
	v_mul_f32_e32 v171, v152, v149
	ds_read_u16_d16_hi v130, v121 offset:17600
	ds_read_u16_d16_hi v138, v122 offset:17600
	ds_read_u16_d16_hi v146, v123 offset:17600
	v_cvt_pk_bf16_f32 v151, v170, v171
	ds_write_b16 v123, v151 offset:15200
	ds_write_b16_d16_hi v123, v151 offset:15600
	s_waitcnt lgkmcnt(15)
	v_fma_f32 v150, -v152, v126, v152
	v_add_f32_e32 v152, v150, v134
	v_mul_f32_e32 v170, v152, v142
	ds_read_u16_d16_hi v131, v121 offset:18000
	ds_read_u16_d16_hi v139, v122 offset:18000
	ds_read_u16_d16_hi v147, v123 offset:18000
	s_waitcnt lgkmcnt(15)
	v_fma_f32 v150, -v152, v127, v152
	v_add_f32_e32 v152, v150, v135
	v_mul_f32_e32 v171, v152, v143
	ds_read_u16_d16_hi v132, v121 offset:18400
	ds_read_u16_d16_hi v140, v122 offset:18400
	ds_read_u16_d16_hi v148, v123 offset:18400
	v_cvt_pk_bf16_f32 v151, v170, v171
	ds_write_b16 v123, v151 offset:16000
	ds_write_b16_d16_hi v123, v151 offset:16400
	s_waitcnt lgkmcnt(15)
	v_fma_f32 v150, -v152, v128, v152
	v_add_f32_e32 v152, v150, v136
	v_mul_f32_e32 v170, v152, v144
	ds_read_u16_d16_hi v133, v121 offset:18800
	ds_read_u16_d16_hi v141, v122 offset:18800
	ds_read_u16_d16_hi v149, v123 offset:18800
	s_waitcnt lgkmcnt(15)
	v_fma_f32 v150, -v152, v129, v152
	v_add_f32_e32 v152, v150, v137
	v_mul_f32_e32 v171, v152, v145
	ds_read_u16_d16_hi v126, v121 offset:19200
	ds_read_u16_d16_hi v134, v122 offset:19200
	ds_read_u16_d16_hi v142, v123 offset:19200
	v_cvt_pk_bf16_f32 v151, v170, v171
	ds_write_b16 v123, v151 offset:16800
	ds_write_b16_d16_hi v123, v151 offset:17200
	s_waitcnt lgkmcnt(15)
	v_fma_f32 v150, -v152, v130, v152
	v_add_f32_e32 v152, v150, v138
	v_mul_f32_e32 v170, v152, v146
	ds_read_u16_d16_hi v127, v121 offset:19600
	ds_read_u16_d16_hi v135, v122 offset:19600
	ds_read_u16_d16_hi v143, v123 offset:19600
	s_waitcnt lgkmcnt(15)
	v_fma_f32 v150, -v152, v131, v152
	v_add_f32_e32 v152, v150, v139
	v_mul_f32_e32 v171, v152, v147
	ds_read_u16_d16_hi v128, v121 offset:20000
	ds_read_u16_d16_hi v136, v122 offset:20000
	ds_read_u16_d16_hi v144, v123 offset:20000
	v_cvt_pk_bf16_f32 v151, v170, v171
	ds_write_b16 v123, v151 offset:17600
	ds_write_b16_d16_hi v123, v151 offset:18000
	s_waitcnt lgkmcnt(15)
	v_fma_f32 v150, -v152, v132, v152
	v_add_f32_e32 v152, v150, v140
	v_mul_f32_e32 v170, v152, v148
	ds_read_u16_d16_hi v129, v121 offset:20400
	ds_read_u16_d16_hi v137, v122 offset:20400
	ds_read_u16_d16_hi v145, v123 offset:20400
	s_waitcnt lgkmcnt(15)
; #define LAS __attribute__((address_space(3)))
; DI unsigned pk2(float a, float b) { f32x2 v = {a, b}; bf2_t r = __builtin_convertvector(v, bf2_t); return __builtin_bit_cast(unsigned, r); }
; DI void phase_rglru(const Params& p, unsigned char* shm) {
;     ...
;             if (tid < 192) {
; #pragma unroll 8
;                 for (int r = 0; r < 64; ++r) {
;                     const float om = __uint_as_float((unsigned)*(const LAS bf16_t*)(lds + LAo + r * TR + tid * 2) << 16);
;                     const float bt = __uint_as_float((unsigned)*(const LAS bf16_t*)(lds + BTo + r * TR + tid * 2) << 16);
;                     const float g = __uint_as_float((unsigned)*(const LAS bf16_t*)(lds + GT + r * TR + tid * 2) << 16);
;                     hst = (hst - om * hst) + bt;
;                     *(LAS bf16_t*)(lds + GT + r * TR + tid * 2) = (bf16_t)(pk2(hst * g, 0.f) & 0xffffu);
;                 }
	v_fma_f32 v150, -v152, v133, v152
	v_add_f32_e32 v152, v150, v141
	v_mul_f32_e32 v171, v152, v149
	ds_read_u16_d16_hi v130, v121 offset:20800
	ds_read_u16_d16_hi v138, v122 offset:20800
	ds_read_u16_d16_hi v146, v123 offset:20800
	v_cvt_pk_bf16_f32 v151, v170, v171
	ds_write_b16 v123, v151 offset:18400
	ds_write_b16_d16_hi v123, v151 offset:18800
	s_waitcnt lgkmcnt(15)
	v_fma_f32 v150, -v152, v126, v152
	v_add_f32_e32 v152, v150, v134
	v_mul_f32_e32 v170, v152, v142
	ds_read_u16_d16_hi v131, v121 offset:21200
	ds_read_u16_d16_hi v139, v122 offset:21200
	ds_read_u16_d16_hi v147, v123 offset:21200
	s_waitcnt lgkmcnt(15)
	v_fma_f32 v150, -v152, v127, v152
	v_add_f32_e32 v152, v150, v135
	v_mul_f32_e32 v171, v152, v143
	ds_read_u16_d16_hi v132, v121 offset:21600
	ds_read_u16_d16_hi v140, v122 offset:21600
	ds_read_u16_d16_hi v148, v123 offset:21600
	v_cvt_pk_bf16_f32 v151, v170, v171
	ds_write_b16 v123, v151 offset:19200
	ds_write_b16_d16_hi v123, v151 offset:19600
	s_waitcnt lgkmcnt(15)
	v_fma_f32 v150, -v152, v128, v152
	v_add_f32_e32 v152, v150, v136
	v_mul_f32_e32 v170, v152, v144
	ds_read_u16_d16_hi v133, v121 offset:22000
	ds_read_u16_d16_hi v141, v122 offset:22000
	ds_read_u16_d16_hi v149, v123 offset:22000
	s_waitcnt lgkmcnt(15)
	v_fma_f32 v150, -v152, v129, v152
	v_add_f32_e32 v152, v150, v137
	v_mul_f32_e32 v171, v152, v145
	ds_read_u16_d16_hi v126, v121 offset:22400
	ds_read_u16_d16_hi v134, v122 offset:22400
	ds_read_u16_d16_hi v142, v123 offset:22400
	v_cvt_pk_bf16_f32 v151, v170, v171
	ds_write_b16 v123, v151 offset:20000
	ds_write_b16_d16_hi v123, v151 offset:20400
	s_waitcnt lgkmcnt(15)
	v_fma_f32 v150, -v152, v130, v152
	v_add_f32_e32 v152, v150, v138
	v_mul_f32_e32 v170, v152, v146
	ds_read_u16_d16_hi v127, v121 offset:22800
	ds_read_u16_d16_hi v135, v122 offset:22800
	ds_read_u16_d16_hi v143, v123 offset:22800
	s_waitcnt lgkmcnt(15)
	v_fma_f32 v150, -v152, v131, v152
	v_add_f32_e32 v152, v150, v139
	v_mul_f32_e32 v171, v152, v147
	ds_read_u16_d16_hi v128, v121 offset:23200
	ds_read_u16_d16_hi v136, v122 offset:23200
	ds_read_u16_d16_hi v144, v123 offset:23200
	v_cvt_pk_bf16_f32 v151, v170, v171
	ds_write_b16 v123, v151 offset:20800
	ds_write_b16_d16_hi v123, v151 offset:21200
	s_waitcnt lgkmcnt(15)
	v_fma_f32 v150, -v152, v132, v152
	v_add_f32_e32 v152, v150, v140
	v_mul_f32_e32 v170, v152, v148
	ds_read_u16_d16_hi v129, v121 offset:23600
	ds_read_u16_d16_hi v137, v122 offset:23600
	ds_read_u16_d16_hi v145, v123 offset:23600
	s_waitcnt lgkmcnt(15)
	v_fma_f32 v150, -v152, v133, v152
	v_add_f32_e32 v152, v150, v141
	v_mul_f32_e32 v171, v152, v149
	ds_read_u16_d16_hi v130, v121 offset:24000
	ds_read_u16_d16_hi v138, v122 offset:24000
	ds_read_u16_d16_hi v146, v123 offset:24000
	v_cvt_pk_bf16_f32 v151, v170, v171
	ds_write_b16 v123, v151 offset:21600
	ds_write_b16_d16_hi v123, v151 offset:22000
	s_waitcnt lgkmcnt(15)
	v_fma_f32 v150, -v152, v126, v152
	v_add_f32_e32 v152, v150, v134
	v_mul_f32_e32 v170, v152, v142
	ds_read_u16_d16_hi v131, v121 offset:24400
	ds_read_u16_d16_hi v139, v122 offset:24400
	ds_read_u16_d16_hi v147, v123 offset:24400
	s_waitcnt lgkmcnt(15)
	v_fma_f32 v150, -v152, v127, v152
	v_add_f32_e32 v152, v150, v135
	v_mul_f32_e32 v171, v152, v143
	ds_read_u16_d16_hi v132, v121 offset:24800
	ds_read_u16_d16_hi v140, v122 offset:24800
	ds_read_u16_d16_hi v148, v123 offset:24800
	v_cvt_pk_bf16_f32 v151, v170, v171
	ds_write_b16 v123, v151 offset:22400
	ds_write_b16_d16_hi v123, v151 offset:22800
	s_waitcnt lgkmcnt(15)
	v_fma_f32 v150, -v152, v128, v152
	v_add_f32_e32 v152, v150, v136
	v_mul_f32_e32 v170, v152, v144
	ds_read_u16_d16_hi v133, v121 offset:25200
	ds_read_u16_d16_hi v141, v122 offset:25200
	ds_read_u16_d16_hi v149, v123 offset:25200
	s_waitcnt lgkmcnt(15)
	v_fma_f32 v150, -v152, v129, v152
	v_add_f32_e32 v152, v150, v137
	v_mul_f32_e32 v171, v152, v145
	v_cvt_pk_bf16_f32 v151, v170, v171
	ds_write_b16 v123, v151 offset:23200
	ds_write_b16_d16_hi v123, v151 offset:23600
	s_waitcnt lgkmcnt(15)
	v_fma_f32 v150, -v152, v130, v152
	v_add_f32_e32 v152, v150, v138
	v_mul_f32_e32 v170, v152, v146
	s_waitcnt lgkmcnt(10)
	v_fma_f32 v150, -v152, v131, v152
	v_add_f32_e32 v152, v150, v139
	v_mul_f32_e32 v171, v152, v147
	v_cvt_pk_bf16_f32 v151, v170, v171
	ds_write_b16 v123, v151 offset:24000
	ds_write_b16_d16_hi v123, v151 offset:24400
	s_waitcnt lgkmcnt(9)
	v_fma_f32 v150, -v152, v132, v152
	v_add_f32_e32 v152, v150, v140
	v_mul_f32_e32 v170, v152, v148
	s_waitcnt lgkmcnt(4)
	v_fma_f32 v150, -v152, v133, v152
	v_add_f32_e32 v152, v150, v141
	v_mul_f32_e32 v171, v152, v149
	v_cvt_pk_bf16_f32 v151, v170, v171
	ds_write_b16 v123, v151 offset:24800
	ds_write_b16_d16_hi v123, v151 offset:25200
	s_branch .LBB0_842
